# GEMM main loops: next k-tile address math + 8 loads hoisted above the LDS-publish barrier (cross-segment overlap), 6 loops
# speedup vs baseline: 1.0063x; 1.0041x over previous
; DI void gemm_mainloop(const bf16* __restrict__ A, int lda, const bf16* __restrict__ Bt, int ldb, int K, int m0, int n0,
;                       bf16* As, bf16* Bs, f32x16& acc0, f32x16& acc1, f32x16& acc2, f32x16& acc3) {
;     ...
;   for (int k0 = 0; k0 < K; k0 += 128) {
;     __syncthreads();
;     gt_store(t0, asw, bsw);
;     __syncthreads();
;     if (k0 + 128 < K) gt_load(t0, ap, bp, lda, ldb, KW(k0 + 128));
.LBB0_229:
	s_add_u32 s28, s20, 0x80
	s_addc_u32 s29, s21, 0
	s_cmpk_gt_u32 s20, 0x37f
	s_barrier
	s_waitcnt vmcnt(13)
	ds_write_b128 v140, v[72:75]
	ds_write_b128 v140, v[64:67] offset:4608
	ds_write_b128 v140, v[68:71] offset:9216
	s_waitcnt vmcnt(11)
	ds_write_b128 v140, v[80:83] offset:13824
	ds_write_b128 v140, v[76:79] offset:18432
	s_waitcnt vmcnt(10)
	ds_write_b128 v140, v[84:87] offset:23040
	s_waitcnt vmcnt(9)
	ds_write_b128 v140, v[96:99] offset:27648
	s_waitcnt vmcnt(8)
	ds_write_b128 v140, v[100:103] offset:32256
	s_cbranch_scc1 .Lmy_gb_0a
	s_cmp_lt_i32 s28, s15
	s_cselect_b32 s1, 0, -1
	s_cselect_b32 s0, 0, 0xfffffc00
	s_add_u32 s30, s18, s20
	s_addc_u32 s31, s19, s21
	s_add_u32 s0, s30, s0
	s_addc_u32 s1, s31, s1
	s_lshl_b64 s[0:1], s[0:1], 1
	v_lshl_add_u64 v[72:73], v[136:137], 0, s[0:1]
	v_add_co_u32_e32 v64, vcc, s48, v72
	v_lshl_add_u64 v[96:97], v[138:139], 0, s[0:1]
	s_nop 0
	v_addc_co_u32_e32 v65, vcc, 0, v73, vcc
	v_add_co_u32_e32 v68, vcc, 0x20000, v72
	s_nop 1
	v_addc_co_u32_e32 v69, vcc, 0, v73, vcc
	v_add_co_u32_e32 v80, vcc, 0x30000, v72
	global_load_dwordx4 v[64:67], v[64:65], off offset:256
	s_nop 0
	global_load_dwordx4 v[68:71], v[68:69], off offset:256
	v_addc_co_u32_e32 v81, vcc, 0, v73, vcc
	v_add_co_u32_e32 v84, vcc, 0x10000, v96
	global_load_dwordx4 v[72:75], v[72:73], off offset:256
	s_nop 0
	global_load_dwordx4 v[76:79], v[96:97], off offset:256
	v_addc_co_u32_e32 v85, vcc, 0, v97, vcc
	v_add_co_u32_e32 v98, vcc, 0x20000, v96
	global_load_dwordx4 v[80:83], v[80:81], off offset:256
	s_nop 0
	global_load_dwordx4 v[84:87], v[84:85], off offset:256
	v_addc_co_u32_e32 v99, vcc, 0, v97, vcc
	v_add_co_u32_e32 v100, vcc, 0x30000, v96
	s_nop 1
	v_addc_co_u32_e32 v101, vcc, 0, v97, vcc
	global_load_dwordx4 v[96:99], v[98:99], off offset:256
	s_nop 0
	global_load_dwordx4 v[100:103], v[100:101], off offset:256

; #define MFMA(a, b, c) __builtin_amdgcn_mfma_f32_32x32x16_bf16((a), (b), (c), 0, 0, 0)
; DI void gt_compute(const bf16* asr, const bf16* bsr, f32x16& acc0, f32x16& acc1, f32x16& acc2, f32x16& acc3) {
;   bf16x8 a[4], b0[4], b1[4], b2[4], b3[4];
; #pragma unroll
;   for (int kk = 0; kk < 4; ++kk) {
;     a[kk] = *(const bf16x8*)(asr + kk * 16);
;     b0[kk] = *(const bf16x8*)(bsr + kk * 16);
;     b1[kk] = *(const bf16x8*)(bsr + 32 * LDT + kk * 16);
;     b2[kk] = *(const bf16x8*)(bsr + 64 * LDT + kk * 16);
;     b3[kk] = *(const bf16x8*)(bsr + 96 * LDT + kk * 16);
;   }
;   __builtin_amdgcn_sched_barrier(0);
;   __builtin_amdgcn_s_setprio(2);
; #pragma unroll
;   for (int kk = 0; kk < 4; ++kk) {
;     acc0 = MFMA(a[kk], b0[kk], acc0); acc1 = MFMA(a[kk], b1[kk], acc1); acc2 = MFMA(a[kk], b2[kk], acc2); acc3 = MFMA(a[kk], b3[kk], acc3);
;   }
;   __builtin_amdgcn_s_setprio(0);
;   __builtin_amdgcn_sched_barrier(0);
; DI void gemm_mainloop(const bf16* __restrict__ A, int lda, const bf16* __restrict__ Bt, int ldb, int K, int m0, int n0,
;                       bf16* As, bf16* Bs, f32x16& acc0, f32x16& acc1, f32x16& acc2, f32x16& acc3) {
;     ...
;     gt_compute(asr, bsr, acc0, acc1, acc2, acc3);
;     __syncthreads();
;     gt_store(t1, asw, bsw);
;     __syncthreads();
;     if (k0 + 192 < K) gt_load(t1, ap, bp, lda, ldb, KW(k0 + 192));
;     gt_compute(asr, bsr, acc0, acc1, acc2, acc3);
.LBB0_231:
	ds_read_b128 v[146:149], v142
	ds_read_b128 v[150:153], v142 offset:32
	ds_read_b128 v[154:157], v130 offset:18432
	ds_read_b128 v[162:165], v130 offset:18464
	ds_read_b128 v[166:169], v130 offset:23040
	ds_read_b128 v[170:173], v130 offset:23072
	ds_read_b128 v[174:177], v130 offset:27648
	ds_read_b128 v[178:181], v130 offset:27680
	ds_read_b128 v[182:185], v130 offset:32256
	ds_read_b128 v[186:189], v130 offset:32288
	ds_read_b128 v[190:193], v142 offset:64
	ds_read_b128 v[194:197], v142 offset:96
	ds_read_b128 v[198:201], v130 offset:18496
	ds_read_b128 v[202:205], v130 offset:18528
	ds_read_b128 v[206:209], v130 offset:23104
	ds_read_b128 v[210:213], v130 offset:23136
	ds_read_b128 v[214:217], v130 offset:27712
	ds_read_b128 v[218:221], v130 offset:27744
	ds_read_b128 v[222:225], v130 offset:32320
	ds_read_b128 v[226:229], v130 offset:32352
	s_waitcnt lgkmcnt(14)
	v_mfma_f32_32x32x16_bf16 v[48:63], v[146:149], v[154:157], v[48:63]
	v_mfma_f32_32x32x16_bf16 v[32:47], v[146:149], v[166:169], v[32:47]
	s_waitcnt lgkmcnt(13)
	v_mfma_f32_32x32x16_bf16 v[16:31], v[146:149], v[174:177], v[16:31]
	s_waitcnt lgkmcnt(11)
	v_mfma_f32_32x32x16_bf16 v[0:15], v[146:149], v[182:185], v[0:15]
	v_mfma_f32_32x32x16_bf16 v[48:63], v[150:153], v[162:165], v[48:63]
	v_mfma_f32_32x32x16_bf16 v[32:47], v[150:153], v[170:173], v[32:47]
	v_mfma_f32_32x32x16_bf16 v[16:31], v[150:153], v[178:181], v[16:31]
	s_waitcnt lgkmcnt(10)
	v_mfma_f32_32x32x16_bf16 v[0:15], v[150:153], v[186:189], v[0:15]
	s_waitcnt lgkmcnt(7)
	v_mfma_f32_32x32x16_bf16 v[48:63], v[190:193], v[198:201], v[48:63]
	s_waitcnt lgkmcnt(5)
	v_mfma_f32_32x32x16_bf16 v[32:47], v[190:193], v[206:209], v[32:47]
	s_waitcnt lgkmcnt(3)
	v_mfma_f32_32x32x16_bf16 v[16:31], v[190:193], v[214:217], v[16:31]
	s_waitcnt lgkmcnt(1)
	v_mfma_f32_32x32x16_bf16 v[0:15], v[190:193], v[222:225], v[0:15]
	v_mfma_f32_32x32x16_bf16 v[48:63], v[194:197], v[202:205], v[48:63]
	v_mfma_f32_32x32x16_bf16 v[32:47], v[194:197], v[210:213], v[32:47]
	v_mfma_f32_32x32x16_bf16 v[16:31], v[194:197], v[218:221], v[16:31]
	s_waitcnt lgkmcnt(0)
	v_mfma_f32_32x32x16_bf16 v[0:15], v[194:197], v[226:229], v[0:15]
	s_cmpk_gt_u32 s20, 0x33f
	s_barrier
	s_waitcnt vmcnt(5)
	ds_write_b128 v140, v[104:107]
	ds_write_b128 v140, v[88:91] offset:4608
	ds_write_b128 v140, v[92:95] offset:9216
	s_waitcnt vmcnt(3)
	ds_write_b128 v140, v[112:115] offset:13824
	ds_write_b128 v140, v[108:111] offset:18432
	s_waitcnt vmcnt(2)
	ds_write_b128 v140, v[116:119] offset:23040
	s_waitcnt vmcnt(1)
	ds_write_b128 v140, v[120:123] offset:27648
	s_waitcnt vmcnt(0)
	ds_write_b128 v140, v[124:127] offset:32256
	s_cbranch_scc1 .Lmy_gb_0b
	s_cmp_lt_i32 s20, s17
	s_cselect_b32 s1, 0, -1
	s_cselect_b32 s0, 0, 0xfffffc00
	s_add_u32 s20, s18, s20
	s_addc_u32 s21, s19, s21
	s_add_u32 s0, s20, s0
	s_addc_u32 s1, s21, s1
	s_lshl_b64 s[0:1], s[0:1], 1
	v_lshl_add_u64 v[104:105], v[136:137], 0, s[0:1]
	v_add_co_u32_e32 v106, vcc, s48, v104
	v_lshl_add_u64 v[120:121], v[138:139], 0, s[0:1]
	s_nop 0
	v_addc_co_u32_e32 v107, vcc, 0, v105, vcc
	v_add_co_u32_e32 v108, vcc, 0x20000, v104
	s_nop 1
	v_addc_co_u32_e32 v109, vcc, 0, v105, vcc
	v_add_co_u32_e32 v112, vcc, 0x30000, v104
	global_load_dwordx4 v[88:91], v[106:107], off offset:384
	global_load_dwordx4 v[92:95], v[108:109], off offset:384
	v_addc_co_u32_e32 v113, vcc, 0, v105, vcc
	v_add_co_u32_e32 v116, vcc, 0x10000, v120
	global_load_dwordx4 v[104:107], v[104:105], off offset:384
	s_nop 0
	global_load_dwordx4 v[108:111], v[120:121], off offset:384
	v_addc_co_u32_e32 v117, vcc, 0, v121, vcc
	v_add_co_u32_e32 v122, vcc, 0x20000, v120
	global_load_dwordx4 v[112:115], v[112:113], off offset:384
	s_nop 0
	global_load_dwordx4 v[116:119], v[116:117], off offset:384
	v_addc_co_u32_e32 v123, vcc, 0, v121, vcc
	v_add_co_u32_e32 v124, vcc, 0x30000, v120
	s_nop 1
	v_addc_co_u32_e32 v125, vcc, 0, v121, vcc
	global_load_dwordx4 v[120:123], v[122:123], off offset:384
	s_nop 0
	global_load_dwordx4 v[124:127], v[124:125], off offset:384
.Lmy_gb_0b:
	s_waitcnt lgkmcnt(0)
	s_barrier
	s_branch .LBB0_228

; DI void gemm_mainloop(const bf16* __restrict__ A, int lda, const bf16* __restrict__ Bt, int ldb, int K, int m0, int n0,
;                       bf16* As, bf16* Bs, f32x16& acc0, f32x16& acc1, f32x16& acc2, f32x16& acc3) {
;     ...
;   for (int k0 = 0; k0 < K; k0 += 128) {
;     __syncthreads();
;     gt_store(t0, asw, bsw);
;     __syncthreads();
;     if (k0 + 128 < K) gt_load(t0, ap, bp, lda, ldb, KW(k0 + 128));
.LBB0_481:
	s_add_u32 s34, s30, 0x80
	s_addc_u32 s35, s31, 0
	s_cmpk_gt_u32 s30, 0x37f
	s_waitcnt vmcnt(63) expcnt(7) lgkmcnt(15)
	s_barrier
	s_waitcnt vmcnt(13)
	ds_write_b128 v136, v[72:75]
	ds_write_b128 v136, v[64:67] offset:4608
	ds_write_b128 v136, v[68:71] offset:9216
	s_waitcnt vmcnt(11)
	ds_write_b128 v136, v[80:83] offset:13824
	ds_write_b128 v136, v[76:79] offset:18432
	s_waitcnt vmcnt(10)
	ds_write_b128 v136, v[84:87] offset:23040
	s_waitcnt vmcnt(9)
	ds_write_b128 v136, v[96:99] offset:27648
	s_waitcnt vmcnt(8)
	ds_write_b128 v136, v[104:107] offset:32256
	s_cbranch_scc1 .Lmy_gb_1a
	s_cmp_lt_i32 s34, s44
	s_cselect_b32 s7, 0, -1
	s_cselect_b32 s6, 0, 0xfffffc00
	s_add_u32 s46, s28, s30
	s_addc_u32 s47, s29, s31
	s_add_u32 s6, s46, s6
	s_addc_u32 s7, s47, s7
	s_lshl_b64 s[6:7], s[6:7], 1
	v_lshl_add_u64 v[72:73], v[132:133], 0, s[6:7]
	v_add_co_u32_e32 v64, vcc, s4, v72
	v_lshl_add_u64 v[96:97], v[134:135], 0, s[6:7]
	s_nop 0
	v_addc_co_u32_e32 v65, vcc, 0, v73, vcc
	v_add_co_u32_e32 v68, vcc, 0x20000, v72
	s_nop 1
	v_addc_co_u32_e32 v69, vcc, 0, v73, vcc
	v_add_co_u32_e32 v80, vcc, 0x30000, v72
	global_load_dwordx4 v[64:67], v[64:65], off offset:256
	s_nop 0
	global_load_dwordx4 v[68:71], v[68:69], off offset:256
	v_addc_co_u32_e32 v81, vcc, 0, v73, vcc
	v_add_co_u32_e32 v84, vcc, 0x10000, v96
	global_load_dwordx4 v[72:75], v[72:73], off offset:256
	s_nop 0
	global_load_dwordx4 v[76:79], v[96:97], off offset:256
	v_addc_co_u32_e32 v85, vcc, 0, v97, vcc
	v_add_co_u32_e32 v98, vcc, 0x20000, v96
	global_load_dwordx4 v[80:83], v[80:81], off offset:256
	s_nop 0
	global_load_dwordx4 v[84:87], v[84:85], off offset:256
	v_addc_co_u32_e32 v99, vcc, 0, v97, vcc
	v_add_co_u32_e32 v104, vcc, 0x30000, v96
	s_nop 1
	v_addc_co_u32_e32 v105, vcc, 0, v97, vcc
	global_load_dwordx4 v[96:99], v[98:99], off offset:256
	s_nop 0
	global_load_dwordx4 v[104:107], v[104:105], off offset:256

; #define MFMA(a, b, c) __builtin_amdgcn_mfma_f32_32x32x16_bf16((a), (b), (c), 0, 0, 0)
; DI void gt_compute(const bf16* asr, const bf16* bsr, f32x16& acc0, f32x16& acc1, f32x16& acc2, f32x16& acc3) {
;   bf16x8 a[4], b0[4], b1[4], b2[4], b3[4];
; #pragma unroll
;   for (int kk = 0; kk < 4; ++kk) {
;     a[kk] = *(const bf16x8*)(asr + kk * 16);
;     b0[kk] = *(const bf16x8*)(bsr + kk * 16);
;     b1[kk] = *(const bf16x8*)(bsr + 32 * LDT + kk * 16);
;     b2[kk] = *(const bf16x8*)(bsr + 64 * LDT + kk * 16);
;     b3[kk] = *(const bf16x8*)(bsr + 96 * LDT + kk * 16);
;   }
;   __builtin_amdgcn_sched_barrier(0);
;   __builtin_amdgcn_s_setprio(2);
; #pragma unroll
;   for (int kk = 0; kk < 4; ++kk) {
;     acc0 = MFMA(a[kk], b0[kk], acc0); acc1 = MFMA(a[kk], b1[kk], acc1); acc2 = MFMA(a[kk], b2[kk], acc2); acc3 = MFMA(a[kk], b3[kk], acc3);
;   }
;   __builtin_amdgcn_s_setprio(0);
;   __builtin_amdgcn_sched_barrier(0);
; DI void gemm_mainloop(const bf16* __restrict__ A, int lda, const bf16* __restrict__ Bt, int ldb, int K, int m0, int n0,
;                       bf16* As, bf16* Bs, f32x16& acc0, f32x16& acc1, f32x16& acc2, f32x16& acc3) {
;     ...
;     gt_compute(asr, bsr, acc0, acc1, acc2, acc3);
;     __syncthreads();
;     gt_store(t1, asw, bsw);
;     __syncthreads();
;     if (k0 + 192 < K) gt_load(t1, ap, bp, lda, ldb, KW(k0 + 192));
;     gt_compute(asr, bsr, acc0, acc1, acc2, acc3);
.LBB0_483:
	ds_read_b128 v[142:145], v138
	ds_read_b128 v[146:149], v138 offset:32
	ds_read_b128 v[150:153], v128 offset:18432
	ds_read_b128 v[154:157], v128 offset:18464
	ds_read_b128 v[166:169], v128 offset:23040
	ds_read_b128 v[170:173], v128 offset:23072
	ds_read_b128 v[174:177], v128 offset:27648
	ds_read_b128 v[178:181], v128 offset:27680
	ds_read_b128 v[182:185], v128 offset:32256
	ds_read_b128 v[186:189], v128 offset:32288
	ds_read_b128 v[190:193], v138 offset:64
	ds_read_b128 v[194:197], v138 offset:96
	ds_read_b128 v[198:201], v128 offset:18496
	ds_read_b128 v[202:205], v128 offset:18528
	ds_read_b128 v[206:209], v128 offset:23104
	ds_read_b128 v[210:213], v128 offset:23136
	ds_read_b128 v[214:217], v128 offset:27712
	ds_read_b128 v[228:231], v128 offset:27744
	ds_read_b128 v[232:235], v128 offset:32320
	ds_read_b128 v[236:239], v128 offset:32352
	s_waitcnt lgkmcnt(14)
	v_mfma_f32_32x32x16_bf16 v[48:63], v[142:145], v[150:153], v[48:63]
	v_mfma_f32_32x32x16_bf16 v[32:47], v[142:145], v[166:169], v[32:47]
	s_waitcnt lgkmcnt(13)
	v_mfma_f32_32x32x16_bf16 v[16:31], v[142:145], v[174:177], v[16:31]
	s_waitcnt lgkmcnt(11)
	v_mfma_f32_32x32x16_bf16 v[0:15], v[142:145], v[182:185], v[0:15]
	v_mfma_f32_32x32x16_bf16 v[48:63], v[146:149], v[154:157], v[48:63]
	v_mfma_f32_32x32x16_bf16 v[32:47], v[146:149], v[170:173], v[32:47]
	v_mfma_f32_32x32x16_bf16 v[16:31], v[146:149], v[178:181], v[16:31]
	s_waitcnt lgkmcnt(10)
	v_mfma_f32_32x32x16_bf16 v[0:15], v[146:149], v[186:189], v[0:15]
	s_waitcnt lgkmcnt(7)
	v_mfma_f32_32x32x16_bf16 v[48:63], v[190:193], v[198:201], v[48:63]
	s_waitcnt lgkmcnt(5)
	v_mfma_f32_32x32x16_bf16 v[32:47], v[190:193], v[206:209], v[32:47]
	s_waitcnt lgkmcnt(3)
	v_mfma_f32_32x32x16_bf16 v[16:31], v[190:193], v[214:217], v[16:31]
	s_waitcnt lgkmcnt(1)
	v_mfma_f32_32x32x16_bf16 v[0:15], v[190:193], v[232:235], v[0:15]
	v_mfma_f32_32x32x16_bf16 v[48:63], v[194:197], v[202:205], v[48:63]
	v_mfma_f32_32x32x16_bf16 v[32:47], v[194:197], v[210:213], v[32:47]
	v_mfma_f32_32x32x16_bf16 v[16:31], v[194:197], v[228:231], v[16:31]
	s_waitcnt lgkmcnt(0)
	v_mfma_f32_32x32x16_bf16 v[0:15], v[194:197], v[236:239], v[0:15]
	s_cmpk_gt_u32 s30, 0x33f
	s_barrier
	s_waitcnt vmcnt(5)
	ds_write_b128 v136, v[100:103]
	ds_write_b128 v136, v[88:91] offset:4608
	ds_write_b128 v136, v[92:95] offset:9216
	s_waitcnt vmcnt(3)
	ds_write_b128 v136, v[112:115] offset:13824
	ds_write_b128 v136, v[108:111] offset:18432
	s_waitcnt vmcnt(2)
	ds_write_b128 v136, v[116:119] offset:23040
	s_waitcnt vmcnt(1)
	ds_write_b128 v136, v[120:123] offset:27648
	s_waitcnt vmcnt(0)
	ds_write_b128 v136, v[124:127] offset:32256
	s_cbranch_scc1 .Lmy_gb_1b
	s_cmp_lt_i32 s30, s45
	s_cselect_b32 s7, 0, -1
	s_cselect_b32 s6, 0, 0xfffffc00
	s_add_u32 s30, s28, s30
	s_addc_u32 s31, s29, s31
	s_add_u32 s6, s30, s6
	s_addc_u32 s7, s31, s7
	s_lshl_b64 s[6:7], s[6:7], 1
	v_lshl_add_u64 v[100:101], v[132:133], 0, s[6:7]
	v_add_co_u32_e32 v88, vcc, s4, v100
	v_lshl_add_u64 v[120:121], v[134:135], 0, s[6:7]
	s_nop 0
	v_addc_co_u32_e32 v89, vcc, 0, v101, vcc
	v_add_co_u32_e32 v92, vcc, 0x20000, v100
	s_nop 1
	v_addc_co_u32_e32 v93, vcc, 0, v101, vcc
	v_add_co_u32_e32 v112, vcc, 0x30000, v100
	global_load_dwordx4 v[88:91], v[88:89], off offset:384
	s_nop 0
	global_load_dwordx4 v[92:95], v[92:93], off offset:384
	v_addc_co_u32_e32 v113, vcc, 0, v101, vcc
	v_add_co_u32_e32 v116, vcc, 0x10000, v120
	global_load_dwordx4 v[100:103], v[100:101], off offset:384
	s_nop 0
	global_load_dwordx4 v[108:111], v[120:121], off offset:384
	v_addc_co_u32_e32 v117, vcc, 0, v121, vcc
	v_add_co_u32_e32 v122, vcc, 0x20000, v120
	global_load_dwordx4 v[112:115], v[112:113], off offset:384
	s_nop 0
	global_load_dwordx4 v[116:119], v[116:117], off offset:384
	v_addc_co_u32_e32 v123, vcc, 0, v121, vcc
	v_add_co_u32_e32 v124, vcc, 0x30000, v120
	s_nop 1
	v_addc_co_u32_e32 v125, vcc, 0, v121, vcc
	global_load_dwordx4 v[120:123], v[122:123], off offset:384
	s_nop 0
	global_load_dwordx4 v[124:127], v[124:125], off offset:384

; DI void gemm_mainloop(const bf16* __restrict__ A, int lda, const bf16* __restrict__ Bt, int ldb, int K, int m0, int n0,
;                       bf16* As, bf16* Bs, f32x16& acc0, f32x16& acc1, f32x16& acc2, f32x16& acc3) {
;     ...
;   for (int k0 = 0; k0 < K; k0 += 128) {
;     __syncthreads();
;     gt_store(t0, asw, bsw);
;     __syncthreads();
;     if (k0 + 128 < K) gt_load(t0, ap, bp, lda, ldb, KW(k0 + 128));
.LBB0_614:
	s_add_u32 s60, s58, 0x80
	s_addc_u32 s61, s59, 0
	s_cmpk_gt_u32 s58, 0x37f
	s_waitcnt vmcnt(63) expcnt(7) lgkmcnt(15)
	s_barrier
	s_waitcnt vmcnt(13)
	ds_write_b128 v142, v[72:75]
	ds_write_b128 v142, v[64:67] offset:4608
	ds_write_b128 v142, v[68:71] offset:9216
	s_waitcnt vmcnt(11)
	ds_write_b128 v142, v[80:83] offset:13824
	ds_write_b128 v142, v[76:79] offset:18432
	s_waitcnt vmcnt(10)
	ds_write_b128 v142, v[84:87] offset:23040
	s_waitcnt vmcnt(9)
	ds_write_b128 v142, v[96:99] offset:27648
	s_waitcnt vmcnt(8)
	ds_write_b128 v142, v[104:107] offset:32256
	s_cbranch_scc1 .Lmy_gb_2a
	s_cmp_lt_i32 s60, s86
	s_cselect_b32 s0, 0, -1
	s_cselect_b32 s1, 0, 0xfffffc00
	s_add_u32 s6, s28, s58
	s_addc_u32 s7, s29, s59
	s_add_u32 s6, s6, s1
	s_addc_u32 s7, s7, s0
	s_lshl_b64 s[6:7], s[6:7], 1
	v_lshl_add_u64 v[72:73], v[138:139], 0, s[6:7]
	v_add_co_u32_e32 v64, vcc, s68, v72
	v_lshl_add_u64 v[96:97], v[140:141], 0, s[6:7]
	s_nop 0
	v_addc_co_u32_e32 v65, vcc, 0, v73, vcc
	v_add_co_u32_e32 v68, vcc, 0x20000, v72
	s_nop 1
	v_addc_co_u32_e32 v69, vcc, 0, v73, vcc
	v_add_co_u32_e32 v80, vcc, 0x30000, v72
	global_load_dwordx4 v[64:67], v[64:65], off offset:256
	s_nop 0
	global_load_dwordx4 v[68:71], v[68:69], off offset:256
	v_addc_co_u32_e32 v81, vcc, 0, v73, vcc
	v_add_co_u32_e32 v84, vcc, 0x10000, v96
	global_load_dwordx4 v[72:75], v[72:73], off offset:256
	s_nop 0
	global_load_dwordx4 v[76:79], v[96:97], off offset:256
	v_addc_co_u32_e32 v85, vcc, 0, v97, vcc
	v_add_co_u32_e32 v98, vcc, 0x20000, v96
	global_load_dwordx4 v[80:83], v[80:81], off offset:256
	s_nop 0
	global_load_dwordx4 v[84:87], v[84:85], off offset:256
	v_addc_co_u32_e32 v99, vcc, 0, v97, vcc
	v_add_co_u32_e32 v104, vcc, 0x30000, v96
	s_nop 1
	v_addc_co_u32_e32 v105, vcc, 0, v97, vcc
	global_load_dwordx4 v[96:99], v[98:99], off offset:256
	s_nop 0
	global_load_dwordx4 v[104:107], v[104:105], off offset:256

; #define MFMA(a, b, c) __builtin_amdgcn_mfma_f32_32x32x16_bf16((a), (b), (c), 0, 0, 0)
; DI void gt_compute(const bf16* asr, const bf16* bsr, f32x16& acc0, f32x16& acc1, f32x16& acc2, f32x16& acc3) {
;   bf16x8 a[4], b0[4], b1[4], b2[4], b3[4];
; #pragma unroll
;   for (int kk = 0; kk < 4; ++kk) {
;     a[kk] = *(const bf16x8*)(asr + kk * 16);
;     b0[kk] = *(const bf16x8*)(bsr + kk * 16);
;     b1[kk] = *(const bf16x8*)(bsr + 32 * LDT + kk * 16);
;     b2[kk] = *(const bf16x8*)(bsr + 64 * LDT + kk * 16);
;     b3[kk] = *(const bf16x8*)(bsr + 96 * LDT + kk * 16);
;   }
;   __builtin_amdgcn_sched_barrier(0);
;   __builtin_amdgcn_s_setprio(2);
; #pragma unroll
;   for (int kk = 0; kk < 4; ++kk) {
;     acc0 = MFMA(a[kk], b0[kk], acc0); acc1 = MFMA(a[kk], b1[kk], acc1); acc2 = MFMA(a[kk], b2[kk], acc2); acc3 = MFMA(a[kk], b3[kk], acc3);
;   }
;   __builtin_amdgcn_s_setprio(0);
;   __builtin_amdgcn_sched_barrier(0);
; DI void gemm_mainloop(const bf16* __restrict__ A, int lda, const bf16* __restrict__ Bt, int ldb, int K, int m0, int n0,
;                       bf16* As, bf16* Bs, f32x16& acc0, f32x16& acc1, f32x16& acc2, f32x16& acc3) {
;     ...
;     gt_compute(asr, bsr, acc0, acc1, acc2, acc3);
;     __syncthreads();
;     gt_store(t1, asw, bsw);
;     __syncthreads();
;     if (k0 + 192 < K) gt_load(t1, ap, bp, lda, ldb, KW(k0 + 192));
;     gt_compute(asr, bsr, acc0, acc1, acc2, acc3);
.LBB0_616:
	ds_read_b128 v[156:159], v144
	ds_read_b128 v[162:165], v144 offset:32
	ds_read_b128 v[166:169], v128 offset:18432
	ds_read_b128 v[170:173], v128 offset:18464
	ds_read_b128 v[174:177], v128 offset:23040
	ds_read_b128 v[178:181], v128 offset:23072
	ds_read_b128 v[182:185], v128 offset:27648
	ds_read_b128 v[186:189], v128 offset:27680
	ds_read_b128 v[190:193], v128 offset:32256
	ds_read_b128 v[194:197], v128 offset:32288
	ds_read_b128 v[198:201], v144 offset:64
	ds_read_b128 v[202:205], v144 offset:96
	ds_read_b128 v[206:209], v128 offset:18496
	ds_read_b128 v[210:213], v128 offset:18528
	ds_read_b128 v[214:217], v128 offset:23104
	ds_read_b128 v[228:231], v128 offset:23136
	ds_read_b128 v[232:235], v128 offset:27712
	ds_read_b128 v[236:239], v128 offset:27744
	ds_read_b128 v[240:243], v128 offset:32320
	ds_read_b128 v[244:247], v128 offset:32352
	s_waitcnt lgkmcnt(14)
	v_mfma_f32_32x32x16_bf16 v[32:47], v[156:159], v[166:169], v[32:47]
	v_mfma_f32_32x32x16_bf16 v[48:63], v[156:159], v[174:177], v[48:63]
	s_waitcnt lgkmcnt(13)
	v_mfma_f32_32x32x16_bf16 v[16:31], v[156:159], v[182:185], v[16:31]
	s_waitcnt lgkmcnt(11)
	v_mfma_f32_32x32x16_bf16 v[0:15], v[156:159], v[190:193], v[0:15]
	v_mfma_f32_32x32x16_bf16 v[32:47], v[162:165], v[170:173], v[32:47]
	v_mfma_f32_32x32x16_bf16 v[48:63], v[162:165], v[178:181], v[48:63]
	v_mfma_f32_32x32x16_bf16 v[16:31], v[162:165], v[186:189], v[16:31]
	s_waitcnt lgkmcnt(10)
	v_mfma_f32_32x32x16_bf16 v[0:15], v[162:165], v[194:197], v[0:15]
	s_waitcnt lgkmcnt(7)
	v_mfma_f32_32x32x16_bf16 v[32:47], v[198:201], v[206:209], v[32:47]
	s_waitcnt lgkmcnt(5)
	v_mfma_f32_32x32x16_bf16 v[48:63], v[198:201], v[214:217], v[48:63]
	s_waitcnt lgkmcnt(3)
	v_mfma_f32_32x32x16_bf16 v[16:31], v[198:201], v[232:235], v[16:31]
	s_waitcnt lgkmcnt(1)
	v_mfma_f32_32x32x16_bf16 v[0:15], v[198:201], v[240:243], v[0:15]
	v_mfma_f32_32x32x16_bf16 v[32:47], v[202:205], v[210:213], v[32:47]
	v_mfma_f32_32x32x16_bf16 v[48:63], v[202:205], v[228:231], v[48:63]
	v_mfma_f32_32x32x16_bf16 v[16:31], v[202:205], v[236:239], v[16:31]
	s_waitcnt lgkmcnt(0)
	v_mfma_f32_32x32x16_bf16 v[0:15], v[202:205], v[244:247], v[0:15]
	s_cmpk_gt_u32 s58, 0x33f
	s_barrier
	s_waitcnt vmcnt(5)
	ds_write_b128 v142, v[100:103]
	ds_write_b128 v142, v[88:91] offset:4608
	ds_write_b128 v142, v[92:95] offset:9216
	s_waitcnt vmcnt(3)
	ds_write_b128 v142, v[112:115] offset:13824
	ds_write_b128 v142, v[108:111] offset:18432
	s_waitcnt vmcnt(2)
	ds_write_b128 v142, v[116:119] offset:23040
	s_waitcnt vmcnt(1)
	ds_write_b128 v142, v[120:123] offset:27648
	s_waitcnt vmcnt(0)
	ds_write_b128 v142, v[124:127] offset:32256
	s_cbranch_scc1 .Lmy_gb_2b
	s_cmp_lt_i32 s58, s87
	s_cselect_b32 s0, 0, -1
	s_cselect_b32 s1, 0, 0xfffffc00
	s_add_u32 s6, s28, s58
	s_addc_u32 s7, s29, s59
	s_add_u32 s6, s6, s1
	s_addc_u32 s7, s7, s0
	s_lshl_b64 s[6:7], s[6:7], 1
	v_lshl_add_u64 v[100:101], v[138:139], 0, s[6:7]
	v_add_co_u32_e32 v88, vcc, s68, v100
	v_lshl_add_u64 v[120:121], v[140:141], 0, s[6:7]
	s_nop 0
	v_addc_co_u32_e32 v89, vcc, 0, v101, vcc
	v_add_co_u32_e32 v92, vcc, 0x20000, v100
	s_nop 1
	v_addc_co_u32_e32 v93, vcc, 0, v101, vcc
	v_add_co_u32_e32 v112, vcc, 0x30000, v100
	global_load_dwordx4 v[88:91], v[88:89], off offset:384
	s_nop 0
	global_load_dwordx4 v[92:95], v[92:93], off offset:384
	v_addc_co_u32_e32 v113, vcc, 0, v101, vcc
	v_add_co_u32_e32 v116, vcc, 0x10000, v120
	global_load_dwordx4 v[100:103], v[100:101], off offset:384
	s_nop 0
	global_load_dwordx4 v[108:111], v[120:121], off offset:384
	v_addc_co_u32_e32 v117, vcc, 0, v121, vcc
	v_add_co_u32_e32 v122, vcc, 0x20000, v120
	global_load_dwordx4 v[112:115], v[112:113], off offset:384
	s_nop 0
	global_load_dwordx4 v[116:119], v[116:117], off offset:384
	v_addc_co_u32_e32 v123, vcc, 0, v121, vcc
	v_add_co_u32_e32 v124, vcc, 0x30000, v120
	s_nop 1
	v_addc_co_u32_e32 v125, vcc, 0, v121, vcc
	global_load_dwordx4 v[120:123], v[122:123], off offset:384
	s_nop 0
	global_load_dwordx4 v[124:127], v[124:125], off offset:384

; DI void gemm_mainloop(const bf16* __restrict__ A, int lda, const bf16* __restrict__ Bt, int ldb, int K, int m0, int n0,
;                       bf16* As, bf16* Bs, f32x16& acc0, f32x16& acc1, f32x16& acc2, f32x16& acc3) {
;     ...
;   for (int k0 = 0; k0 < K; k0 += 128) {
;     __syncthreads();
;     gt_store(t0, asw, bsw);
;     __syncthreads();
;     if (k0 + 128 < K) gt_load(t0, ap, bp, lda, ldb, KW(k0 + 128));
.LBB0_951:
	s_add_u32 s50, s48, 0x80
	s_addc_u32 s51, s49, 0
	s_cmpk_gt_u32 s48, 0x37f
	s_waitcnt vmcnt(63) expcnt(7) lgkmcnt(15)
	s_barrier
	s_waitcnt vmcnt(13)
	ds_write_b128 v150, v[72:75]
	ds_write_b128 v150, v[64:67] offset:4608
	ds_write_b128 v150, v[68:71] offset:9216
	s_waitcnt vmcnt(11)
	ds_write_b128 v150, v[80:83] offset:13824
	ds_write_b128 v150, v[76:79] offset:18432
	s_waitcnt vmcnt(10)
	ds_write_b128 v150, v[84:87] offset:23040
	s_waitcnt vmcnt(9)
	ds_write_b128 v150, v[96:99] offset:27648
	s_waitcnt vmcnt(8)
	ds_write_b128 v150, v[104:107] offset:32256
	s_cbranch_scc1 .Lmy_gb_3a
	s_cmp_lt_i32 s50, s30
	s_cselect_b32 s7, 0, -1
	s_cselect_b32 s6, 0, 0xfffffc00
	s_add_u32 s65, s28, s48
	s_addc_u32 s66, s29, s49
	s_add_u32 s6, s65, s6
	s_addc_u32 s7, s66, s7
	s_lshl_b64 s[6:7], s[6:7], 1
	v_lshl_add_u64 v[72:73], v[146:147], 0, s[6:7]
	v_add_co_u32_e32 v64, vcc, s59, v72
	v_lshl_add_u64 v[96:97], v[148:149], 0, s[6:7]
	s_nop 0
	v_addc_co_u32_e32 v65, vcc, 0, v73, vcc
	v_add_co_u32_e32 v68, vcc, 0x20000, v72
	s_nop 1
	v_addc_co_u32_e32 v69, vcc, 0, v73, vcc
	v_add_co_u32_e32 v80, vcc, 0x30000, v72
	global_load_dwordx4 v[64:67], v[64:65], off offset:256
	s_nop 0
	global_load_dwordx4 v[68:71], v[68:69], off offset:256
	v_addc_co_u32_e32 v81, vcc, 0, v73, vcc
	v_add_co_u32_e32 v84, vcc, 0x10000, v96
	global_load_dwordx4 v[72:75], v[72:73], off offset:256
	s_nop 0
	global_load_dwordx4 v[76:79], v[96:97], off offset:256
	v_addc_co_u32_e32 v85, vcc, 0, v97, vcc
	v_add_co_u32_e32 v98, vcc, 0x20000, v96
	global_load_dwordx4 v[80:83], v[80:81], off offset:256
	s_nop 0
	global_load_dwordx4 v[84:87], v[84:85], off offset:256
	v_addc_co_u32_e32 v99, vcc, 0, v97, vcc
	v_add_co_u32_e32 v104, vcc, 0x30000, v96
	s_nop 1
	v_addc_co_u32_e32 v105, vcc, 0, v97, vcc
	global_load_dwordx4 v[96:99], v[98:99], off offset:256
	s_nop 0
	global_load_dwordx4 v[104:107], v[104:105], off offset:256

; #define MFMA(a, b, c) __builtin_amdgcn_mfma_f32_32x32x16_bf16((a), (b), (c), 0, 0, 0)
; DI void gt_compute(const bf16* asr, const bf16* bsr, f32x16& acc0, f32x16& acc1, f32x16& acc2, f32x16& acc3) {
;   bf16x8 a[4], b0[4], b1[4], b2[4], b3[4];
; #pragma unroll
;   for (int kk = 0; kk < 4; ++kk) {
;     a[kk] = *(const bf16x8*)(asr + kk * 16);
;     b0[kk] = *(const bf16x8*)(bsr + kk * 16);
;     b1[kk] = *(const bf16x8*)(bsr + 32 * LDT + kk * 16);
;     b2[kk] = *(const bf16x8*)(bsr + 64 * LDT + kk * 16);
;     b3[kk] = *(const bf16x8*)(bsr + 96 * LDT + kk * 16);
;   }
;   __builtin_amdgcn_sched_barrier(0);
;   __builtin_amdgcn_s_setprio(2);
; #pragma unroll
;   for (int kk = 0; kk < 4; ++kk) {
;     acc0 = MFMA(a[kk], b0[kk], acc0); acc1 = MFMA(a[kk], b1[kk], acc1); acc2 = MFMA(a[kk], b2[kk], acc2); acc3 = MFMA(a[kk], b3[kk], acc3);
;   }
;   __builtin_amdgcn_s_setprio(0);
;   __builtin_amdgcn_sched_barrier(0);
; DI void gemm_mainloop(const bf16* __restrict__ A, int lda, const bf16* __restrict__ Bt, int ldb, int K, int m0, int n0,
;                       bf16* As, bf16* Bs, f32x16& acc0, f32x16& acc1, f32x16& acc2, f32x16& acc3) {
;     ...
;     gt_compute(asr, bsr, acc0, acc1, acc2, acc3);
;     __syncthreads();
;     gt_store(t1, asw, bsw);
;     __syncthreads();
;     if (k0 + 192 < K) gt_load(t1, ap, bp, lda, ldb, KW(k0 + 192));
;     gt_compute(asr, bsr, acc0, acc1, acc2, acc3);
.LBB0_953:
	ds_read_b128 v[174:177], v152
	ds_read_b128 v[178:181], v152 offset:32
	ds_read_b128 v[182:185], v130 offset:18432
	ds_read_b128 v[186:189], v130 offset:18464
	ds_read_b128 v[190:193], v130 offset:23040
	ds_read_b128 v[194:197], v130 offset:23072
	ds_read_b128 v[198:201], v130 offset:27648
	ds_read_b128 v[202:205], v130 offset:27680
	ds_read_b128 v[206:209], v130 offset:32256
	ds_read_b128 v[210:213], v130 offset:32288
	ds_read_b128 v[214:217], v152 offset:64
	ds_read_b128 v[226:229], v152 offset:96
	ds_read_b128 v[230:233], v130 offset:18496
	ds_read_b128 v[234:237], v130 offset:18528
	ds_read_b128 v[238:241], v130 offset:23104
	ds_read_b128 v[242:245], v130 offset:23136
	ds_read_b128 v[246:249], v130 offset:27712
	ds_read_b128 v[250:253], v130 offset:27744
	ds_read_b128 v[156:159], v130 offset:32320
	ds_read_b128 v[162:165], v130 offset:32352
	s_waitcnt lgkmcnt(14)
	v_mfma_f32_32x32x16_bf16 v[48:63], v[174:177], v[182:185], v[48:63]
	v_mfma_f32_32x32x16_bf16 v[16:31], v[174:177], v[190:193], v[16:31]
	s_waitcnt lgkmcnt(13)
	v_mfma_f32_32x32x16_bf16 v[32:47], v[174:177], v[198:201], v[32:47]
	s_waitcnt lgkmcnt(11)
	v_mfma_f32_32x32x16_bf16 v[0:15], v[174:177], v[206:209], v[0:15]
	v_mfma_f32_32x32x16_bf16 v[48:63], v[178:181], v[186:189], v[48:63]
	v_mfma_f32_32x32x16_bf16 v[16:31], v[178:181], v[194:197], v[16:31]
	v_mfma_f32_32x32x16_bf16 v[32:47], v[178:181], v[202:205], v[32:47]
	s_waitcnt lgkmcnt(10)
	v_mfma_f32_32x32x16_bf16 v[0:15], v[178:181], v[210:213], v[0:15]
	s_waitcnt lgkmcnt(7)
	v_mfma_f32_32x32x16_bf16 v[48:63], v[214:217], v[230:233], v[48:63]
	s_waitcnt lgkmcnt(5)
	v_mfma_f32_32x32x16_bf16 v[16:31], v[214:217], v[238:241], v[16:31]
	s_waitcnt lgkmcnt(3)
	v_mfma_f32_32x32x16_bf16 v[32:47], v[214:217], v[246:249], v[32:47]
	s_waitcnt lgkmcnt(1)
	v_mfma_f32_32x32x16_bf16 v[0:15], v[214:217], v[156:159], v[0:15]
	v_mfma_f32_32x32x16_bf16 v[48:63], v[226:229], v[234:237], v[48:63]
	v_mfma_f32_32x32x16_bf16 v[16:31], v[226:229], v[242:245], v[16:31]
	v_mfma_f32_32x32x16_bf16 v[32:47], v[226:229], v[250:253], v[32:47]
	s_waitcnt lgkmcnt(0)
	v_mfma_f32_32x32x16_bf16 v[0:15], v[226:229], v[162:165], v[0:15]
	s_cmpk_gt_u32 s48, 0x33f
	s_barrier
	s_waitcnt vmcnt(5)
	ds_write_b128 v150, v[100:103]
	ds_write_b128 v150, v[88:91] offset:4608
	ds_write_b128 v150, v[92:95] offset:9216
	s_waitcnt vmcnt(3)
	ds_write_b128 v150, v[112:115] offset:13824
	ds_write_b128 v150, v[108:111] offset:18432
	s_waitcnt vmcnt(2)
	ds_write_b128 v150, v[116:119] offset:23040
	s_waitcnt vmcnt(1)
	ds_write_b128 v150, v[120:123] offset:27648
	s_waitcnt vmcnt(0)
	ds_write_b128 v150, v[124:127] offset:32256
	s_cbranch_scc1 .Lmy_gb_3b
	s_cmp_lt_i32 s48, s31
	s_cselect_b32 s7, 0, -1
	s_cselect_b32 s6, 0, 0xfffffc00
	s_add_u32 s48, s28, s48
	s_addc_u32 s49, s29, s49
	s_add_u32 s6, s48, s6
	s_addc_u32 s7, s49, s7
	s_lshl_b64 s[6:7], s[6:7], 1
	v_lshl_add_u64 v[100:101], v[146:147], 0, s[6:7]
	v_add_co_u32_e32 v88, vcc, s59, v100
	v_lshl_add_u64 v[120:121], v[148:149], 0, s[6:7]
	s_nop 0
	v_addc_co_u32_e32 v89, vcc, 0, v101, vcc
	v_add_co_u32_e32 v92, vcc, 0x20000, v100
	s_nop 1
	v_addc_co_u32_e32 v93, vcc, 0, v101, vcc
	v_add_co_u32_e32 v112, vcc, 0x30000, v100
	global_load_dwordx4 v[88:91], v[88:89], off offset:384
	s_nop 0
	global_load_dwordx4 v[92:95], v[92:93], off offset:384
	v_addc_co_u32_e32 v113, vcc, 0, v101, vcc
	v_add_co_u32_e32 v116, vcc, 0x10000, v120
	global_load_dwordx4 v[100:103], v[100:101], off offset:384
	s_nop 0
	global_load_dwordx4 v[108:111], v[120:121], off offset:384
	v_addc_co_u32_e32 v117, vcc, 0, v121, vcc
	v_add_co_u32_e32 v122, vcc, 0x20000, v120
	global_load_dwordx4 v[112:115], v[112:113], off offset:384
	s_nop 0
	global_load_dwordx4 v[116:119], v[116:117], off offset:384
	v_addc_co_u32_e32 v123, vcc, 0, v121, vcc
	v_add_co_u32_e32 v124, vcc, 0x30000, v120
	s_nop 1
	v_addc_co_u32_e32 v125, vcc, 0, v121, vcc
	global_load_dwordx4 v[120:123], v[122:123], off offset:384
	s_nop 0
	global_load_dwordx4 v[124:127], v[124:125], off offset:384

; DI void gemm_mainloop(const bf16* __restrict__ A, int lda, const bf16* __restrict__ Bt, int ldb, int K, int m0, int n0,
;                       bf16* As, bf16* Bs, f32x16& acc0, f32x16& acc1, f32x16& acc2, f32x16& acc3) {
;     ...
;   for (int k0 = 0; k0 < K; k0 += 128) {
;     __syncthreads();
;     gt_store(t0, asw, bsw);
;     __syncthreads();
;     if (k0 + 128 < K) gt_load(t0, ap, bp, lda, ldb, KW(k0 + 128));
.LBB0_1319:
	s_add_u32 s16, s14, 0x80
	s_addc_u32 s17, s15, 0
	s_cmpk_gt_u32 s14, 0x37f
	s_waitcnt vmcnt(63) expcnt(7) lgkmcnt(15)
	s_barrier
	s_waitcnt vmcnt(13)
	ds_write_b128 v136, v[72:75]
	ds_write_b128 v136, v[64:67] offset:4608
	ds_write_b128 v136, v[68:71] offset:9216
	s_waitcnt vmcnt(11)
	ds_write_b128 v136, v[80:83] offset:13824
	ds_write_b128 v136, v[76:79] offset:18432
	s_waitcnt vmcnt(10)
	ds_write_b128 v136, v[84:87] offset:23040
	s_waitcnt vmcnt(9)
	ds_write_b128 v136, v[96:99] offset:27648
	s_waitcnt vmcnt(8)
	ds_write_b128 v136, v[100:103] offset:32256
	s_cbranch_scc1 .Lmy_gb_4a
	s_cmp_lt_i32 s16, s25
	s_cselect_b32 s0, 0, -1
	s_cselect_b32 s1, 0, 0xfffffc00
	s_add_u32 s6, s12, s14
	s_addc_u32 s7, s13, s15
	s_add_u32 s6, s6, s1
	s_addc_u32 s7, s7, s0
	s_lshl_b64 s[6:7], s[6:7], 1
	v_lshl_add_u64 v[72:73], v[132:133], 0, s[6:7]
	v_add_co_u32_e32 v64, vcc, s4, v72
	v_lshl_add_u64 v[96:97], v[134:135], 0, s[6:7]
	s_nop 0
	v_addc_co_u32_e32 v65, vcc, 0, v73, vcc
	v_add_co_u32_e32 v68, vcc, 0x20000, v72
	s_nop 1
	v_addc_co_u32_e32 v69, vcc, 0, v73, vcc
	v_add_co_u32_e32 v80, vcc, 0x30000, v72
	global_load_dwordx4 v[64:67], v[64:65], off offset:256
	s_nop 0
	global_load_dwordx4 v[68:71], v[68:69], off offset:256
	v_addc_co_u32_e32 v81, vcc, 0, v73, vcc
	v_add_co_u32_e32 v84, vcc, 0x10000, v96
	global_load_dwordx4 v[72:75], v[72:73], off offset:256
	s_nop 0
	global_load_dwordx4 v[76:79], v[96:97], off offset:256
	v_addc_co_u32_e32 v85, vcc, 0, v97, vcc
	v_add_co_u32_e32 v98, vcc, 0x20000, v96
	global_load_dwordx4 v[80:83], v[80:81], off offset:256
	s_nop 0
	global_load_dwordx4 v[84:87], v[84:85], off offset:256
	v_addc_co_u32_e32 v99, vcc, 0, v97, vcc
	v_add_co_u32_e32 v100, vcc, 0x30000, v96
	s_nop 1
	v_addc_co_u32_e32 v101, vcc, 0, v97, vcc
	global_load_dwordx4 v[96:99], v[98:99], off offset:256
	s_nop 0
	global_load_dwordx4 v[100:103], v[100:101], off offset:256

; #define MFMA(a, b, c) __builtin_amdgcn_mfma_f32_32x32x16_bf16((a), (b), (c), 0, 0, 0)
; DI void gt_compute(const bf16* asr, const bf16* bsr, f32x16& acc0, f32x16& acc1, f32x16& acc2, f32x16& acc3) {
;   bf16x8 a[4], b0[4], b1[4], b2[4], b3[4];
; #pragma unroll
;   for (int kk = 0; kk < 4; ++kk) {
;     a[kk] = *(const bf16x8*)(asr + kk * 16);
;     b0[kk] = *(const bf16x8*)(bsr + kk * 16);
;     b1[kk] = *(const bf16x8*)(bsr + 32 * LDT + kk * 16);
;     b2[kk] = *(const bf16x8*)(bsr + 64 * LDT + kk * 16);
;     b3[kk] = *(const bf16x8*)(bsr + 96 * LDT + kk * 16);
;   }
;   __builtin_amdgcn_sched_barrier(0);
;   __builtin_amdgcn_s_setprio(2);
; #pragma unroll
;   for (int kk = 0; kk < 4; ++kk) {
;     acc0 = MFMA(a[kk], b0[kk], acc0); acc1 = MFMA(a[kk], b1[kk], acc1); acc2 = MFMA(a[kk], b2[kk], acc2); acc3 = MFMA(a[kk], b3[kk], acc3);
;   }
;   __builtin_amdgcn_s_setprio(0);
;   __builtin_amdgcn_sched_barrier(0);
; DI void gemm_mainloop(const bf16* __restrict__ A, int lda, const bf16* __restrict__ Bt, int ldb, int K, int m0, int n0,
;                       bf16* As, bf16* Bs, f32x16& acc0, f32x16& acc1, f32x16& acc2, f32x16& acc3) {
;     ...
;     gt_compute(asr, bsr, acc0, acc1, acc2, acc3);
;     __syncthreads();
;     gt_store(t1, asw, bsw);
;     __syncthreads();
;     if (k0 + 192 < K) gt_load(t1, ap, bp, lda, ldb, KW(k0 + 192));
;     gt_compute(asr, bsr, acc0, acc1, acc2, acc3);
.LBB0_1321:
	ds_read_b128 v[142:145], v138
	ds_read_b128 v[146:149], v138 offset:32
	ds_read_b128 v[150:153], v128 offset:18432
	ds_read_b128 v[154:157], v128 offset:18464
	ds_read_b128 v[162:165], v128 offset:23040
	ds_read_b128 v[166:169], v128 offset:23072
	ds_read_b128 v[170:173], v128 offset:27648
	ds_read_b128 v[174:177], v128 offset:27680
	ds_read_b128 v[178:181], v128 offset:32256
	ds_read_b128 v[182:185], v128 offset:32288
	ds_read_b128 v[186:189], v138 offset:64
	ds_read_b128 v[190:193], v138 offset:96
	ds_read_b128 v[194:197], v128 offset:18496
	ds_read_b128 v[198:201], v128 offset:18528
	ds_read_b128 v[202:205], v128 offset:23104
	ds_read_b128 v[206:209], v128 offset:23136
	ds_read_b128 v[210:213], v128 offset:27712
	ds_read_b128 v[214:217], v128 offset:27744
	ds_read_b128 v[226:229], v128 offset:32320
	ds_read_b128 v[230:233], v128 offset:32352
	s_waitcnt lgkmcnt(14)
	v_mfma_f32_32x32x16_bf16 v[48:63], v[142:145], v[150:153], v[48:63]
	v_mfma_f32_32x32x16_bf16 v[32:47], v[142:145], v[162:165], v[32:47]
	s_waitcnt lgkmcnt(13)
	v_mfma_f32_32x32x16_bf16 v[16:31], v[142:145], v[170:173], v[16:31]
	s_waitcnt lgkmcnt(11)
	v_mfma_f32_32x32x16_bf16 v[0:15], v[142:145], v[178:181], v[0:15]
	v_mfma_f32_32x32x16_bf16 v[48:63], v[146:149], v[154:157], v[48:63]
	v_mfma_f32_32x32x16_bf16 v[32:47], v[146:149], v[166:169], v[32:47]
	v_mfma_f32_32x32x16_bf16 v[16:31], v[146:149], v[174:177], v[16:31]
	s_waitcnt lgkmcnt(10)
	v_mfma_f32_32x32x16_bf16 v[0:15], v[146:149], v[182:185], v[0:15]
	s_waitcnt lgkmcnt(7)
	v_mfma_f32_32x32x16_bf16 v[48:63], v[186:189], v[194:197], v[48:63]
	s_waitcnt lgkmcnt(5)
	v_mfma_f32_32x32x16_bf16 v[32:47], v[186:189], v[202:205], v[32:47]
	s_waitcnt lgkmcnt(3)
	v_mfma_f32_32x32x16_bf16 v[16:31], v[186:189], v[210:213], v[16:31]
	s_waitcnt lgkmcnt(1)
	v_mfma_f32_32x32x16_bf16 v[0:15], v[186:189], v[226:229], v[0:15]
	v_mfma_f32_32x32x16_bf16 v[48:63], v[190:193], v[198:201], v[48:63]
	v_mfma_f32_32x32x16_bf16 v[32:47], v[190:193], v[206:209], v[32:47]
	v_mfma_f32_32x32x16_bf16 v[16:31], v[190:193], v[214:217], v[16:31]
	s_waitcnt lgkmcnt(0)
	v_mfma_f32_32x32x16_bf16 v[0:15], v[190:193], v[230:233], v[0:15]
	s_cmpk_gt_u32 s14, 0x33f
	s_barrier
	s_waitcnt vmcnt(5)
	ds_write_b128 v136, v[104:107]
	ds_write_b128 v136, v[88:91] offset:4608
	ds_write_b128 v136, v[92:95] offset:9216
	s_waitcnt vmcnt(3)
	ds_write_b128 v136, v[112:115] offset:13824
	ds_write_b128 v136, v[108:111] offset:18432
	s_waitcnt vmcnt(2)
	ds_write_b128 v136, v[116:119] offset:23040
	s_waitcnt vmcnt(1)
	ds_write_b128 v136, v[120:123] offset:27648
	s_waitcnt vmcnt(0)
	ds_write_b128 v136, v[124:127] offset:32256
	s_cbranch_scc1 .Lmy_gb_4b
	s_cmp_lt_i32 s14, s28
	s_cselect_b32 s0, 0, -1
	s_cselect_b32 s1, 0, 0xfffffc00
	s_add_u32 s6, s12, s14
	s_addc_u32 s7, s13, s15
	s_add_u32 s6, s6, s1
	s_addc_u32 s7, s7, s0
	s_lshl_b64 s[6:7], s[6:7], 1
	v_lshl_add_u64 v[104:105], v[132:133], 0, s[6:7]
	v_add_co_u32_e32 v88, vcc, s4, v104
	v_lshl_add_u64 v[120:121], v[134:135], 0, s[6:7]
	s_nop 0
	v_addc_co_u32_e32 v89, vcc, 0, v105, vcc
	v_add_co_u32_e32 v92, vcc, 0x20000, v104
	s_nop 1
	v_addc_co_u32_e32 v93, vcc, 0, v105, vcc
	v_add_co_u32_e32 v112, vcc, 0x30000, v104
	global_load_dwordx4 v[88:91], v[88:89], off offset:384
	s_nop 0
	global_load_dwordx4 v[92:95], v[92:93], off offset:384
	v_addc_co_u32_e32 v113, vcc, 0, v105, vcc
	v_add_co_u32_e32 v116, vcc, 0x10000, v120
	global_load_dwordx4 v[104:107], v[104:105], off offset:384
	s_nop 0
	global_load_dwordx4 v[108:111], v[120:121], off offset:384
	v_addc_co_u32_e32 v117, vcc, 0, v121, vcc
	v_add_co_u32_e32 v122, vcc, 0x20000, v120
	global_load_dwordx4 v[112:115], v[112:113], off offset:384
	s_nop 0
	global_load_dwordx4 v[116:119], v[116:117], off offset:384
	v_addc_co_u32_e32 v123, vcc, 0, v121, vcc
	v_add_co_u32_e32 v124, vcc, 0x30000, v120
	s_nop 1
	v_addc_co_u32_e32 v125, vcc, 0, v121, vcc
	global_load_dwordx4 v[120:123], v[122:123], off offset:384
	s_nop 0
	global_load_dwordx4 v[124:127], v[124:125], off offset:384

; DI void gemm_mainloop(const bf16* __restrict__ A, int lda, const bf16* __restrict__ Bt, int ldb, int K, int m0, int n0,
;                       bf16* As, bf16* Bs, f32x16& acc0, f32x16& acc1, f32x16& acc2, f32x16& acc3) {
;     ...
;   for (int k0 = 0; k0 < K; k0 += 128) {
;     __syncthreads();
;     gt_store(t0, asw, bsw);
;     __syncthreads();
;     if (k0 + 128 < K) gt_load(t0, ap, bp, lda, ldb, KW(k0 + 128));
.LBB0_1437:
	s_add_u32 s42, s40, 0x80
	s_addc_u32 s43, s41, 0
	s_cmpk_gt_u32 s40, 0x37f
	s_waitcnt vmcnt(63) expcnt(7) lgkmcnt(15)
	s_barrier
	s_waitcnt vmcnt(13)
	ds_write_b128 v134, v[72:75]
	ds_write_b128 v134, v[64:67] offset:4608
	ds_write_b128 v134, v[68:71] offset:9216
	s_waitcnt vmcnt(11)
	ds_write_b128 v134, v[80:83] offset:13824
	ds_write_b128 v134, v[76:79] offset:18432
	s_waitcnt vmcnt(10)
	ds_write_b128 v134, v[84:87] offset:23040
	s_waitcnt vmcnt(9)
	ds_write_b128 v134, v[96:99] offset:27648
	s_waitcnt vmcnt(8)
	ds_write_b128 v134, v[104:107] offset:32256
	s_cbranch_scc1 .Lmy_gb_5a
	s_cmp_lt_i32 s42, s86
	s_cselect_b32 s1, 0, -1
	s_cselect_b32 s0, 0, 0xfffffc00
	s_add_u32 s2, s28, s40
	s_addc_u32 s3, s29, s41
	s_add_u32 s0, s2, s0
	s_addc_u32 s1, s3, s1
	s_lshl_b64 s[0:1], s[0:1], 1
	v_lshl_add_u64 v[72:73], v[130:131], 0, s[0:1]
	v_add_co_u32_e32 v64, vcc, s46, v72
	v_lshl_add_u64 v[96:97], v[132:133], 0, s[0:1]
	s_nop 0
	v_addc_co_u32_e32 v65, vcc, 0, v73, vcc
	v_add_co_u32_e32 v68, vcc, 0x20000, v72
	s_nop 1
	v_addc_co_u32_e32 v69, vcc, 0, v73, vcc
	v_add_co_u32_e32 v80, vcc, 0x30000, v72
	global_load_dwordx4 v[64:67], v[64:65], off offset:256
	s_nop 0
	global_load_dwordx4 v[68:71], v[68:69], off offset:256
	v_addc_co_u32_e32 v81, vcc, 0, v73, vcc
	v_add_co_u32_e32 v84, vcc, 0x10000, v96
	global_load_dwordx4 v[72:75], v[72:73], off offset:256
	s_nop 0
	global_load_dwordx4 v[76:79], v[96:97], off offset:256
	v_addc_co_u32_e32 v85, vcc, 0, v97, vcc
	v_add_co_u32_e32 v98, vcc, 0x20000, v96
	global_load_dwordx4 v[80:83], v[80:81], off offset:256
	s_nop 0
	global_load_dwordx4 v[84:87], v[84:85], off offset:256
	v_addc_co_u32_e32 v99, vcc, 0, v97, vcc
	v_add_co_u32_e32 v104, vcc, 0x30000, v96
	s_nop 1
	v_addc_co_u32_e32 v105, vcc, 0, v97, vcc
	global_load_dwordx4 v[96:99], v[98:99], off offset:256
	s_nop 0
	global_load_dwordx4 v[104:107], v[104:105], off offset:256

; #define MFMA(a, b, c) __builtin_amdgcn_mfma_f32_32x32x16_bf16((a), (b), (c), 0, 0, 0)
; DI void gt_compute(const bf16* asr, const bf16* bsr, f32x16& acc0, f32x16& acc1, f32x16& acc2, f32x16& acc3) {
;   bf16x8 a[4], b0[4], b1[4], b2[4], b3[4];
; #pragma unroll
;   for (int kk = 0; kk < 4; ++kk) {
;     a[kk] = *(const bf16x8*)(asr + kk * 16);
;     b0[kk] = *(const bf16x8*)(bsr + kk * 16);
;     b1[kk] = *(const bf16x8*)(bsr + 32 * LDT + kk * 16);
;     b2[kk] = *(const bf16x8*)(bsr + 64 * LDT + kk * 16);
;     b3[kk] = *(const bf16x8*)(bsr + 96 * LDT + kk * 16);
;   }
;   __builtin_amdgcn_sched_barrier(0);
;   __builtin_amdgcn_s_setprio(2);
; #pragma unroll
;   for (int kk = 0; kk < 4; ++kk) {
;     acc0 = MFMA(a[kk], b0[kk], acc0); acc1 = MFMA(a[kk], b1[kk], acc1); acc2 = MFMA(a[kk], b2[kk], acc2); acc3 = MFMA(a[kk], b3[kk], acc3);
;   }
;   __builtin_amdgcn_s_setprio(0);
;   __builtin_amdgcn_sched_barrier(0);
; DI void gemm_mainloop(const bf16* __restrict__ A, int lda, const bf16* __restrict__ Bt, int ldb, int K, int m0, int n0,
;                       bf16* As, bf16* Bs, f32x16& acc0, f32x16& acc1, f32x16& acc2, f32x16& acc3) {
;     ...
;     gt_compute(asr, bsr, acc0, acc1, acc2, acc3);
;     __syncthreads();
;     gt_store(t1, asw, bsw);
;     __syncthreads();
;     if (k0 + 192 < K) gt_load(t1, ap, bp, lda, ldb, KW(k0 + 192));
;     gt_compute(asr, bsr, acc0, acc1, acc2, acc3);
.LBB0_1439:
	ds_read_b128 v[148:151], v136
	ds_read_b128 v[152:155], v136 offset:32
	ds_read_b128 v[156:159], v128 offset:18432
	ds_read_b128 v[162:165], v128 offset:18464
	ds_read_b128 v[166:169], v128 offset:23040
	ds_read_b128 v[170:173], v128 offset:23072
	ds_read_b128 v[174:177], v128 offset:27648
	ds_read_b128 v[178:181], v128 offset:27680
	ds_read_b128 v[182:185], v128 offset:32256
	ds_read_b128 v[186:189], v128 offset:32288
	ds_read_b128 v[190:193], v136 offset:64
	ds_read_b128 v[194:197], v136 offset:96
	ds_read_b128 v[198:201], v128 offset:18496
	ds_read_b128 v[202:205], v128 offset:18528
	ds_read_b128 v[206:209], v128 offset:23104
	ds_read_b128 v[210:213], v128 offset:23136
	ds_read_b128 v[214:217], v128 offset:27712
	ds_read_b128 v[226:229], v128 offset:27744
	ds_read_b128 v[230:233], v128 offset:32320
	ds_read_b128 v[234:237], v128 offset:32352
	s_waitcnt lgkmcnt(14)
	v_mfma_f32_32x32x16_bf16 v[32:47], v[148:151], v[156:159], v[32:47]
	v_mfma_f32_32x32x16_bf16 v[48:63], v[148:151], v[166:169], v[48:63]
	s_waitcnt lgkmcnt(13)
	v_mfma_f32_32x32x16_bf16 v[16:31], v[148:151], v[174:177], v[16:31]
	s_waitcnt lgkmcnt(11)
	v_mfma_f32_32x32x16_bf16 v[0:15], v[148:151], v[182:185], v[0:15]
	v_mfma_f32_32x32x16_bf16 v[32:47], v[152:155], v[162:165], v[32:47]
	v_mfma_f32_32x32x16_bf16 v[48:63], v[152:155], v[170:173], v[48:63]
	v_mfma_f32_32x32x16_bf16 v[16:31], v[152:155], v[178:181], v[16:31]
	s_waitcnt lgkmcnt(10)
	v_mfma_f32_32x32x16_bf16 v[0:15], v[152:155], v[186:189], v[0:15]
	s_waitcnt lgkmcnt(7)
	v_mfma_f32_32x32x16_bf16 v[32:47], v[190:193], v[198:201], v[32:47]
	s_waitcnt lgkmcnt(5)
	v_mfma_f32_32x32x16_bf16 v[48:63], v[190:193], v[206:209], v[48:63]
	s_waitcnt lgkmcnt(3)
	v_mfma_f32_32x32x16_bf16 v[16:31], v[190:193], v[214:217], v[16:31]
	s_waitcnt lgkmcnt(1)
	v_mfma_f32_32x32x16_bf16 v[0:15], v[190:193], v[230:233], v[0:15]
	v_mfma_f32_32x32x16_bf16 v[32:47], v[194:197], v[202:205], v[32:47]
	v_mfma_f32_32x32x16_bf16 v[48:63], v[194:197], v[210:213], v[48:63]
	v_mfma_f32_32x32x16_bf16 v[16:31], v[194:197], v[226:229], v[16:31]
	s_waitcnt lgkmcnt(0)
	v_mfma_f32_32x32x16_bf16 v[0:15], v[194:197], v[234:237], v[0:15]
	s_cmpk_gt_u32 s40, 0x33f
	s_barrier
	s_waitcnt vmcnt(5)
	ds_write_b128 v134, v[100:103]
	ds_write_b128 v134, v[88:91] offset:4608
	ds_write_b128 v134, v[92:95] offset:9216
	s_waitcnt vmcnt(3)
	ds_write_b128 v134, v[112:115] offset:13824
	ds_write_b128 v134, v[108:111] offset:18432
	s_waitcnt vmcnt(2)
	ds_write_b128 v134, v[116:119] offset:23040
	s_waitcnt vmcnt(1)
	ds_write_b128 v134, v[120:123] offset:27648
	s_waitcnt vmcnt(0)
	ds_write_b128 v134, v[124:127] offset:32256
	s_cbranch_scc1 .Lmy_gb_5b
	s_cmp_lt_i32 s40, s87
	s_cselect_b32 s1, 0, -1
	s_cselect_b32 s0, 0, 0xfffffc00
	s_add_u32 s2, s28, s40
	s_addc_u32 s3, s29, s41
	s_add_u32 s0, s2, s0
	s_addc_u32 s1, s3, s1
	s_lshl_b64 s[0:1], s[0:1], 1
	v_lshl_add_u64 v[100:101], v[130:131], 0, s[0:1]
	v_add_co_u32_e32 v88, vcc, s46, v100
	v_lshl_add_u64 v[120:121], v[132:133], 0, s[0:1]
	s_nop 0
	v_addc_co_u32_e32 v89, vcc, 0, v101, vcc
	v_add_co_u32_e32 v92, vcc, 0x20000, v100
	s_nop 1
	v_addc_co_u32_e32 v93, vcc, 0, v101, vcc
	v_add_co_u32_e32 v112, vcc, 0x30000, v100
	global_load_dwordx4 v[88:91], v[88:89], off offset:384
	s_nop 0
	global_load_dwordx4 v[92:95], v[92:93], off offset:384
	v_addc_co_u32_e32 v113, vcc, 0, v101, vcc
	v_add_co_u32_e32 v116, vcc, 0x10000, v120
	global_load_dwordx4 v[100:103], v[100:101], off offset:384
	s_nop 0
	global_load_dwordx4 v[108:111], v[120:121], off offset:384
	v_addc_co_u32_e32 v117, vcc, 0, v121, vcc
	v_add_co_u32_e32 v122, vcc, 0x20000, v120
	global_load_dwordx4 v[112:115], v[112:113], off offset:384
	s_nop 0
	global_load_dwordx4 v[116:119], v[116:117], off offset:384
	v_addc_co_u32_e32 v123, vcc, 0, v121, vcc
	v_add_co_u32_e32 v124, vcc, 0x30000, v120
	s_nop 1
	v_addc_co_u32_e32 v125, vcc, 0, v121, vcc
	global_load_dwordx4 v[120:123], v[122:123], off offset:384
	s_nop 0
	global_load_dwordx4 v[124:127], v[124:125], off offset:384
